# k21
# speedup vs baseline: 1.0030x; 1.0030x over previous
; #define PG8_STAGE(bufoff, gbase, voff) do { _Pragma("unroll") for (int _i = 0; _i < 2; ++_i) \
;         __builtin_amdgcn_global_load_lds((const unsigned*)((const char*)(gbase) + (voff)[_i]), (LAS unsigned*)(lds + (bufoff) + ldsw + _i * 8192), 16, 0, 0); } while (0)
; #define PG8_LDA(dst, b, h) do { _Pragma("unroll") for (int m = 0; m < 4; ++m) _Pragma("unroll") for (int k = 0; k < 2; ++k) dst[m][k] = *(const LAS bf16x8*)(lds + PG8_SA(b, h) + aoff + m * 2048 + k * 1024); } while (0)
; #define PG8_LDB(dst, b, h) do { _Pragma("unroll") for (int n = 0; n < 2; ++n) _Pragma("unroll") for (int k = 0; k < 2; ++k) dst[n][k] = *(const LAS bf16x8*)(lds + PG8_SB(b, h) + boff + n * 2048 + k * 1024); } while (0)
; #define PG8_MMA(ai, bj, At, Bt) do { __builtin_amdgcn_s_setprio(1); _Pragma("unroll") for (int m = 0; m < 4; ++m) _Pragma("unroll") for (int n = 0; n < 2; ++n) _Pragma("unroll") for (int k = 0; k < 2; ++k) \
;         acc[ai][bj][m][n] = __builtin_amdgcn_mfma_f32_16x16x32_bf16(Bt[n][k], At[m][k], acc[ai][bj][m][n], 0, 0, 0); __builtin_amdgcn_s_setprio(0); } while (0)
; #define PG8_WAIT_V(n) asm volatile("s_waitcnt vmcnt(" #n ")" ::: "memory")
; #define PG8_WAIT_L(n) asm volatile("s_waitcnt lgkmcnt(" #n ")" ::: "memory")
; #define PG8_BAR __builtin_amdgcn_s_barrier()
; #define PG8_SCHED __builtin_amdgcn_sched_barrier(0)
; template <class Epi, class Sched>
; __device__ __forceinline__ void gemm_phase(LAS unsigned char* lds, const Gemm g, const Sched& S, const Epi& E, int wid_) {
;     ...
;             PG8_LDB(B0, 0, 0); PG8_LDB(B1, 0, 1); PG8_SCHED; PG8_LDA(At, 0, 0); PG8_STAGE(PG8_SA(1, 1), a1 + hstepA, voffA);
;             PG8_WAIT_V(8); PG8_WAIT_L(0); PG8_BAR; PG8_MMA(0, 0, At, B0); PG8_MMA(0, 1, At, B1); PG8_BAR; PG8_SCHED;
;             PG8_LDA(At, 0, 1); PG8_STAGE(PG8_SB(0, 0), b2, voffB); PG8_STAGE(PG8_SB(0, 1), b2 + hstepB, voffB); PG8_STAGE(PG8_SA(0, 0), a2, voffA);
;             PG8_WAIT_V(8); PG8_WAIT_L(0); PG8_BAR; PG8_MMA(1, 0, At, B0); PG8_MMA(1, 1, At, B1); PG8_BAR; PG8_SCHED;
.LBB0_1237:
	s_add_u32 s30, s28, 0x100
	s_addc_u32 s31, s29, 0
	s_add_i32 s12, 0, 0x10000
	s_cmp_eq_u32 s33, 40
	s_cselect_b32 s39, s81, s31
	s_cselect_b32 s38, s82, s30
	s_cselect_b32 s37, s83, s85
	s_cselect_b32 s36, s84, s54
	s_add_i32 s14, 0, 0x14000
	v_add_u32_e32 v142, s12, v182
	v_add_u32_e32 v168, s14, v182
	ds_read_b128 v[130:133], v142
	ds_read_b128 v[134:137], v142 offset:1024
	ds_read_b128 v[138:141], v142 offset:2048
	ds_read_b128 v[142:145], v142 offset:3072
	ds_read_b128 v[146:149], v168
	ds_read_b128 v[150:153], v168 offset:1024
	ds_read_b128 v[164:167], v168 offset:2048
	ds_read_b128 v[168:171], v168 offset:3072
	s_add_i32 m0, s44, 0xc000
	ds_read_b128 v[172:175], v183
	ds_read_b128 v[176:179], v183 offset:1024
	ds_read_b128 v[184:187], v183 offset:2048
	ds_read_b128 v[188:191], v183 offset:3072
	ds_read_b128 v[192:195], v183 offset:4096
	ds_read_b128 v[196:199], v183 offset:5120
	ds_read_b128 v[200:203], v183 offset:6144
	ds_read_b128 v[204:207], v183 offset:7168
	global_load_lds_dwordx4 v160, s[28:29]
	s_add_i32 m0, s44, 0xe000
	s_nop 0
	global_load_lds_dwordx4 v162, s[28:29]
	s_waitcnt vmcnt(8)
	s_waitcnt lgkmcnt(0)
	s_barrier
	s_setprio 1
	s_waitcnt lgkmcnt(0)
	v_mfma_f32_16x16x32_bf16 v[126:129], v[130:133], v[172:175], v[126:129]
	v_mfma_f32_16x16x32_bf16 v[122:125], v[138:141], v[172:175], v[122:125]
	v_mfma_f32_16x16x32_bf16 v[110:113], v[130:133], v[184:187], v[110:113]
	v_mfma_f32_16x16x32_bf16 v[106:109], v[138:141], v[184:187], v[106:109]
	v_mfma_f32_16x16x32_bf16 v[94:97], v[130:133], v[192:195], v[94:97]
	v_mfma_f32_16x16x32_bf16 v[90:93], v[138:141], v[192:195], v[90:93]
	v_mfma_f32_16x16x32_bf16 v[78:81], v[130:133], v[200:203], v[78:81]
	v_mfma_f32_16x16x32_bf16 v[74:77], v[138:141], v[200:203], v[74:77]
	v_mfma_f32_16x16x32_bf16 v[126:129], v[134:137], v[176:179], v[126:129]
	v_mfma_f32_16x16x32_bf16 v[122:125], v[142:145], v[176:179], v[122:125]
	v_mfma_f32_16x16x32_bf16 v[110:113], v[134:137], v[188:191], v[110:113]
	v_mfma_f32_16x16x32_bf16 v[106:109], v[142:145], v[188:191], v[106:109]
	v_mfma_f32_16x16x32_bf16 v[94:97], v[134:137], v[196:199], v[94:97]
	v_mfma_f32_16x16x32_bf16 v[90:93], v[142:145], v[196:199], v[90:93]
	v_mfma_f32_16x16x32_bf16 v[78:81], v[134:137], v[204:207], v[78:81]
	v_mfma_f32_16x16x32_bf16 v[74:77], v[142:145], v[204:207], v[74:77]
	s_setprio 0
	s_setprio 1
	v_mfma_f32_16x16x32_bf16 v[118:121], v[146:149], v[172:175], v[118:121]
	v_mfma_f32_16x16x32_bf16 v[114:117], v[164:167], v[172:175], v[114:117]
	v_mfma_f32_16x16x32_bf16 v[102:105], v[146:149], v[184:187], v[102:105]
	v_mfma_f32_16x16x32_bf16 v[98:101], v[164:167], v[184:187], v[98:101]
	v_mfma_f32_16x16x32_bf16 v[86:89], v[146:149], v[192:195], v[86:89]
	v_mfma_f32_16x16x32_bf16 v[82:85], v[164:167], v[192:195], v[82:85]
	v_mfma_f32_16x16x32_bf16 v[70:73], v[146:149], v[200:203], v[70:73]
	v_mfma_f32_16x16x32_bf16 v[66:69], v[164:167], v[200:203], v[66:69]
	v_mfma_f32_16x16x32_bf16 v[118:121], v[150:153], v[176:179], v[118:121]
	v_mfma_f32_16x16x32_bf16 v[114:117], v[168:171], v[176:179], v[114:117]
	v_mfma_f32_16x16x32_bf16 v[102:105], v[150:153], v[188:191], v[102:105]
	v_mfma_f32_16x16x32_bf16 v[98:101], v[168:171], v[188:191], v[98:101]
	v_mfma_f32_16x16x32_bf16 v[86:89], v[150:153], v[196:199], v[86:89]
	v_mfma_f32_16x16x32_bf16 v[82:85], v[168:171], v[196:199], v[82:85]
	v_mfma_f32_16x16x32_bf16 v[70:73], v[150:153], v[204:207], v[70:73]
	v_mfma_f32_16x16x32_bf16 v[66:69], v[168:171], v[204:207], v[66:69]
	s_setprio 0
	s_barrier
	s_add_i32 s12, s12, s42
	s_mov_b32 m0, s12
	ds_read_b128 v[172:175], v183 offset:16384
	ds_read_b128 v[176:179], v183 offset:17408
	ds_read_b128 v[184:187], v183 offset:18432
	ds_read_b128 v[188:191], v183 offset:19456
	ds_read_b128 v[192:195], v183 offset:20480
	ds_read_b128 v[196:199], v183 offset:21504
	ds_read_b128 v[200:203], v183 offset:22528
	ds_read_b128 v[204:207], v183 offset:23552
	global_load_lds_dwordx4 v0, s[36:37]
	s_add_i32 m0, s12, 0x2000
	s_add_u32 s28, s36, 0xb0000
	s_addc_u32 s29, s37, 0
	s_add_i32 s12, s14, s42
	global_load_lds_dwordx4 v158, s[36:37]
	s_mov_b32 m0, s12
	s_nop 0
	global_load_lds_dwordx4 v0, s[28:29]
	s_add_i32 m0, s12, 0x2000
	s_nop 0
	global_load_lds_dwordx4 v158, s[28:29]
	s_mov_b32 m0, s44
	s_nop 0
	global_load_lds_dwordx4 v154, s[38:39]
	s_mov_b32 m0, s45
	s_nop 0
	global_load_lds_dwordx4 v156, s[38:39]
	s_waitcnt vmcnt(8)
	s_waitcnt lgkmcnt(0)
	s_barrier
	s_setprio 1
	s_waitcnt lgkmcnt(0)
	v_mfma_f32_16x16x32_bf16 v[62:65], v[130:133], v[172:175], v[62:65]
	v_mfma_f32_16x16x32_bf16 v[58:61], v[138:141], v[172:175], v[58:61]
	v_mfma_f32_16x16x32_bf16 v[46:49], v[130:133], v[184:187], v[46:49]
	v_mfma_f32_16x16x32_bf16 v[42:45], v[138:141], v[184:187], v[42:45]
	v_mfma_f32_16x16x32_bf16 v[30:33], v[130:133], v[192:195], v[30:33]
	v_mfma_f32_16x16x32_bf16 v[26:29], v[138:141], v[192:195], v[26:29]
	v_mfma_f32_16x16x32_bf16 v[14:17], v[130:133], v[200:203], v[14:17]
	v_mfma_f32_16x16x32_bf16 v[10:13], v[138:141], v[200:203], v[10:13]
	v_mfma_f32_16x16x32_bf16 v[62:65], v[134:137], v[176:179], v[62:65]
	v_mfma_f32_16x16x32_bf16 v[58:61], v[142:145], v[176:179], v[58:61]
	v_mfma_f32_16x16x32_bf16 v[46:49], v[134:137], v[188:191], v[46:49]
	v_mfma_f32_16x16x32_bf16 v[42:45], v[142:145], v[188:191], v[42:45]
	v_mfma_f32_16x16x32_bf16 v[30:33], v[134:137], v[196:199], v[30:33]
	v_mfma_f32_16x16x32_bf16 v[26:29], v[142:145], v[196:199], v[26:29]
	v_mfma_f32_16x16x32_bf16 v[14:17], v[134:137], v[204:207], v[14:17]
	v_mfma_f32_16x16x32_bf16 v[10:13], v[142:145], v[204:207], v[10:13]
	s_setprio 0
	s_setprio 1
	v_mfma_f32_16x16x32_bf16 v[54:57], v[146:149], v[172:175], v[54:57]
	v_mfma_f32_16x16x32_bf16 v[50:53], v[164:167], v[172:175], v[50:53]
	v_mfma_f32_16x16x32_bf16 v[38:41], v[146:149], v[184:187], v[38:41]
	v_mfma_f32_16x16x32_bf16 v[34:37], v[164:167], v[184:187], v[34:37]
	v_mfma_f32_16x16x32_bf16 v[22:25], v[146:149], v[192:195], v[22:25]
	v_mfma_f32_16x16x32_bf16 v[18:21], v[164:167], v[192:195], v[18:21]
	v_mfma_f32_16x16x32_bf16 v[6:9], v[146:149], v[200:203], v[6:9]
	v_mfma_f32_16x16x32_bf16 v[2:5], v[164:167], v[200:203], v[2:5]
	v_mfma_f32_16x16x32_bf16 v[54:57], v[150:153], v[176:179], v[54:57]
	v_mfma_f32_16x16x32_bf16 v[50:53], v[168:171], v[176:179], v[50:53]
	v_mfma_f32_16x16x32_bf16 v[38:41], v[150:153], v[188:191], v[38:41]
	v_mfma_f32_16x16x32_bf16 v[34:37], v[168:171], v[188:191], v[34:37]
	v_mfma_f32_16x16x32_bf16 v[22:25], v[150:153], v[196:199], v[22:25]
	v_mfma_f32_16x16x32_bf16 v[18:21], v[168:171], v[196:199], v[18:21]
	v_mfma_f32_16x16x32_bf16 v[6:9], v[150:153], v[204:207], v[6:9]
	v_mfma_f32_16x16x32_bf16 v[2:5], v[168:171], v[204:207], v[2:5]
	s_setprio 0
	s_barrier
; #define PG8_STAGE(bufoff, gbase, voff) do { _Pragma("unroll") for (int _i = 0; _i < 2; ++_i) \
;         __builtin_amdgcn_global_load_lds((const unsigned*)((const char*)(gbase) + (voff)[_i]), (LAS unsigned*)(lds + (bufoff) + ldsw + _i * 8192), 16, 0, 0); } while (0)
; #define PG8_LDA(dst, b, h) do { _Pragma("unroll") for (int m = 0; m < 4; ++m) _Pragma("unroll") for (int k = 0; k < 2; ++k) dst[m][k] = *(const LAS bf16x8*)(lds + PG8_SA(b, h) + aoff + m * 2048 + k * 1024); } while (0)
; #define PG8_LDB(dst, b, h) do { _Pragma("unroll") for (int n = 0; n < 2; ++n) _Pragma("unroll") for (int k = 0; k < 2; ++k) dst[n][k] = *(const LAS bf16x8*)(lds + PG8_SB(b, h) + boff + n * 2048 + k * 1024); } while (0)
; #define PG8_MMA(ai, bj, At, Bt) do { __builtin_amdgcn_s_setprio(1); _Pragma("unroll") for (int m = 0; m < 4; ++m) _Pragma("unroll") for (int n = 0; n < 2; ++n) _Pragma("unroll") for (int k = 0; k < 2; ++k) \
;         acc[ai][bj][m][n] = __builtin_amdgcn_mfma_f32_16x16x32_bf16(Bt[n][k], At[m][k], acc[ai][bj][m][n], 0, 0, 0); __builtin_amdgcn_s_setprio(0); } while (0)
; #define PG8_WAIT_V(n) asm volatile("s_waitcnt vmcnt(" #n ")" ::: "memory")
; #define PG8_WAIT_L(n) asm volatile("s_waitcnt lgkmcnt(" #n ")" ::: "memory")
; #define PG8_BAR __builtin_amdgcn_s_barrier()
; #define PG8_SCHED __builtin_amdgcn_sched_barrier(0)
; template <class Epi, class Sched>
; __device__ __forceinline__ void gemm_phase(LAS unsigned char* lds, const Gemm g, const Sched& S, const Epi& E, int wid_) {
;     ...
;             PG8_LDB(B0, 1, 0); PG8_LDB(B1, 1, 1); PG8_SCHED; PG8_LDA(At, 1, 0); PG8_STAGE(PG8_SA(0, 1), a2 + hstepA, voffA);
;             PG8_WAIT_V(8); PG8_WAIT_L(0); PG8_BAR; PG8_MMA(0, 0, At, B0); PG8_MMA(0, 1, At, B1); PG8_BAR; PG8_SCHED;
;             PG8_LDA(At, 1, 1); PG8_STAGE(PG8_SB(1, 0), b3, voffB); PG8_STAGE(PG8_SB(1, 1), b3 + hstepB, voffB); PG8_STAGE(PG8_SA(1, 0), a3, voffA);
;             PG8_WAIT_V(8); PG8_WAIT_L(0); PG8_BAR; PG8_MMA(1, 0, At, B0); PG8_MMA(1, 1, At, B1); PG8_BAR; PG8_SCHED;
;         }
	s_add_i32 s12, 0, 0x18000
	s_add_i32 s14, 0, 0x1c000
	v_add_u32_e32 v142, s12, v182
	v_add_u32_e32 v168, s14, v182
	ds_read_b128 v[130:133], v142
	ds_read_b128 v[134:137], v142 offset:1024
	ds_read_b128 v[138:141], v142 offset:2048
	ds_read_b128 v[142:145], v142 offset:3072
	ds_read_b128 v[146:149], v168
	ds_read_b128 v[150:153], v168 offset:1024
	ds_read_b128 v[164:167], v168 offset:2048
	ds_read_b128 v[168:171], v168 offset:3072
	s_add_u32 s28, s38, 0xb0000
	s_addc_u32 s29, s39, 0
	s_mov_b32 m0, s46
	ds_read_b128 v[172:175], v183 offset:32768
	ds_read_b128 v[176:179], v183 offset:33792
	ds_read_b128 v[184:187], v183 offset:34816
	ds_read_b128 v[188:191], v183 offset:35840
	ds_read_b128 v[192:195], v183 offset:36864
	ds_read_b128 v[196:199], v183 offset:37888
	ds_read_b128 v[200:203], v183 offset:38912
	ds_read_b128 v[204:207], v183 offset:39936
	global_load_lds_dwordx4 v154, s[28:29]
	s_mov_b32 m0, s47
	s_nop 0
	global_load_lds_dwordx4 v156, s[28:29]
	s_waitcnt vmcnt(8)
	s_waitcnt lgkmcnt(0)
	s_barrier
	s_setprio 1
	s_waitcnt lgkmcnt(0)
	v_mfma_f32_16x16x32_bf16 v[126:129], v[130:133], v[172:175], v[126:129]
	v_mfma_f32_16x16x32_bf16 v[122:125], v[138:141], v[172:175], v[122:125]
	v_mfma_f32_16x16x32_bf16 v[110:113], v[130:133], v[184:187], v[110:113]
	v_mfma_f32_16x16x32_bf16 v[106:109], v[138:141], v[184:187], v[106:109]
	v_mfma_f32_16x16x32_bf16 v[94:97], v[130:133], v[192:195], v[94:97]
	v_mfma_f32_16x16x32_bf16 v[90:93], v[138:141], v[192:195], v[90:93]
	v_mfma_f32_16x16x32_bf16 v[78:81], v[130:133], v[200:203], v[78:81]
	v_mfma_f32_16x16x32_bf16 v[74:77], v[138:141], v[200:203], v[74:77]
	v_mfma_f32_16x16x32_bf16 v[126:129], v[134:137], v[176:179], v[126:129]
	v_mfma_f32_16x16x32_bf16 v[122:125], v[142:145], v[176:179], v[122:125]
	v_mfma_f32_16x16x32_bf16 v[110:113], v[134:137], v[188:191], v[110:113]
	v_mfma_f32_16x16x32_bf16 v[106:109], v[142:145], v[188:191], v[106:109]
	v_mfma_f32_16x16x32_bf16 v[94:97], v[134:137], v[196:199], v[94:97]
	v_mfma_f32_16x16x32_bf16 v[90:93], v[142:145], v[196:199], v[90:93]
	v_mfma_f32_16x16x32_bf16 v[78:81], v[134:137], v[204:207], v[78:81]
	v_mfma_f32_16x16x32_bf16 v[74:77], v[142:145], v[204:207], v[74:77]
	s_setprio 0
	s_setprio 1
	v_mfma_f32_16x16x32_bf16 v[118:121], v[146:149], v[172:175], v[118:121]
	v_mfma_f32_16x16x32_bf16 v[114:117], v[164:167], v[172:175], v[114:117]
	v_mfma_f32_16x16x32_bf16 v[102:105], v[146:149], v[184:187], v[102:105]
	v_mfma_f32_16x16x32_bf16 v[98:101], v[164:167], v[184:187], v[98:101]
	v_mfma_f32_16x16x32_bf16 v[86:89], v[146:149], v[192:195], v[86:89]
	v_mfma_f32_16x16x32_bf16 v[82:85], v[164:167], v[192:195], v[82:85]
	v_mfma_f32_16x16x32_bf16 v[70:73], v[146:149], v[200:203], v[70:73]
	v_mfma_f32_16x16x32_bf16 v[66:69], v[164:167], v[200:203], v[66:69]
	v_mfma_f32_16x16x32_bf16 v[118:121], v[150:153], v[176:179], v[118:121]
	v_mfma_f32_16x16x32_bf16 v[114:117], v[168:171], v[176:179], v[114:117]
	v_mfma_f32_16x16x32_bf16 v[102:105], v[150:153], v[188:191], v[102:105]
	v_mfma_f32_16x16x32_bf16 v[98:101], v[168:171], v[188:191], v[98:101]
	v_mfma_f32_16x16x32_bf16 v[86:89], v[150:153], v[196:199], v[86:89]
	v_mfma_f32_16x16x32_bf16 v[82:85], v[168:171], v[196:199], v[82:85]
	v_mfma_f32_16x16x32_bf16 v[70:73], v[150:153], v[204:207], v[70:73]
	v_mfma_f32_16x16x32_bf16 v[66:69], v[168:171], v[204:207], v[66:69]
	s_setprio 0
	s_barrier
	s_add_i32 s12, s12, s42
	s_add_u32 s100, s36, s70
	s_addc_u32 s101, s37, s71
	s_mov_b32 m0, s12
	ds_read_b128 v[172:175], v183 offset:49152
	ds_read_b128 v[176:179], v183 offset:50176
	ds_read_b128 v[184:187], v183 offset:51200
	ds_read_b128 v[188:191], v183 offset:52224
	ds_read_b128 v[192:195], v183 offset:53248
	ds_read_b128 v[196:199], v183 offset:54272
	ds_read_b128 v[200:203], v183 offset:55296
	ds_read_b128 v[204:207], v183 offset:56320
	global_load_lds_dwordx4 v0, s[100:101]
	s_add_i32 m0, s12, 0x2000
	s_add_u32 s28, s36, 0xb0080
	s_addc_u32 s29, s37, 0
	s_add_i32 s12, s14, s42
	global_load_lds_dwordx4 v158, s[100:101]
	s_mov_b32 m0, s12
	s_nop 0
	global_load_lds_dwordx4 v0, s[28:29]
	s_add_i32 m0, s12, 0x2000
	s_nop 0
	global_load_lds_dwordx4 v158, s[28:29]
	s_add_u32 s100, s38, s70
	s_addc_u32 s101, s39, s71
	s_mov_b32 m0, s51
	s_nop 0
	global_load_lds_dwordx4 v154, s[100:101]
	s_mov_b32 m0, s57
	s_nop 0
	global_load_lds_dwordx4 v156, s[100:101]
	s_waitcnt vmcnt(8)
	s_waitcnt lgkmcnt(0)
	s_barrier
	s_setprio 1
	s_waitcnt lgkmcnt(0)
	v_mfma_f32_16x16x32_bf16 v[62:65], v[130:133], v[172:175], v[62:65]
	v_mfma_f32_16x16x32_bf16 v[58:61], v[138:141], v[172:175], v[58:61]
	v_mfma_f32_16x16x32_bf16 v[46:49], v[130:133], v[184:187], v[46:49]
	v_mfma_f32_16x16x32_bf16 v[42:45], v[138:141], v[184:187], v[42:45]
	v_mfma_f32_16x16x32_bf16 v[30:33], v[130:133], v[192:195], v[30:33]
	v_mfma_f32_16x16x32_bf16 v[26:29], v[138:141], v[192:195], v[26:29]
	v_mfma_f32_16x16x32_bf16 v[14:17], v[130:133], v[200:203], v[14:17]
	v_mfma_f32_16x16x32_bf16 v[10:13], v[138:141], v[200:203], v[10:13]
	v_mfma_f32_16x16x32_bf16 v[62:65], v[134:137], v[176:179], v[62:65]
	v_mfma_f32_16x16x32_bf16 v[58:61], v[142:145], v[176:179], v[58:61]
	v_mfma_f32_16x16x32_bf16 v[46:49], v[134:137], v[188:191], v[46:49]
	v_mfma_f32_16x16x32_bf16 v[42:45], v[142:145], v[188:191], v[42:45]
	v_mfma_f32_16x16x32_bf16 v[30:33], v[134:137], v[196:199], v[30:33]
	v_mfma_f32_16x16x32_bf16 v[26:29], v[142:145], v[196:199], v[26:29]
	v_mfma_f32_16x16x32_bf16 v[14:17], v[134:137], v[204:207], v[14:17]
	v_mfma_f32_16x16x32_bf16 v[10:13], v[142:145], v[204:207], v[10:13]
	s_setprio 0
	s_setprio 1
	v_mfma_f32_16x16x32_bf16 v[54:57], v[146:149], v[172:175], v[54:57]
	v_mfma_f32_16x16x32_bf16 v[50:53], v[164:167], v[172:175], v[50:53]
	v_mfma_f32_16x16x32_bf16 v[38:41], v[146:149], v[184:187], v[38:41]
	v_mfma_f32_16x16x32_bf16 v[34:37], v[164:167], v[184:187], v[34:37]
	v_mfma_f32_16x16x32_bf16 v[22:25], v[146:149], v[192:195], v[22:25]
	v_mfma_f32_16x16x32_bf16 v[18:21], v[164:167], v[192:195], v[18:21]
	v_mfma_f32_16x16x32_bf16 v[6:9], v[146:149], v[200:203], v[6:9]
	v_mfma_f32_16x16x32_bf16 v[2:5], v[164:167], v[200:203], v[2:5]
	v_mfma_f32_16x16x32_bf16 v[54:57], v[150:153], v[176:179], v[54:57]
	v_mfma_f32_16x16x32_bf16 v[50:53], v[168:171], v[176:179], v[50:53]
	v_mfma_f32_16x16x32_bf16 v[38:41], v[150:153], v[188:191], v[38:41]
	v_mfma_f32_16x16x32_bf16 v[34:37], v[168:171], v[188:191], v[34:37]
	v_mfma_f32_16x16x32_bf16 v[22:25], v[150:153], v[196:199], v[22:25]
	v_mfma_f32_16x16x32_bf16 v[18:21], v[168:171], v[196:199], v[18:21]
	v_mfma_f32_16x16x32_bf16 v[6:9], v[150:153], v[204:207], v[6:9]
	v_mfma_f32_16x16x32_bf16 v[2:5], v[168:171], v[204:207], v[2:5]
	s_setprio 0
	s_barrier
	s_add_i32 s33, s33, 2
	s_add_u32 s54, s54, 0x100
	s_addc_u32 s85, s85, 0
	s_cmp_gt_u32 s33, 41
	s_mov_b64 s[28:29], s[30:31]
	s_cbranch_scc0 .LBB0_1237
	s_and_b64 vcc, exec, s[18:19]
	s_cbranch_vccz .LBB0_1240
	s_barrier
